# v18
# baseline (speedup 1.0000x reference)
; DI unsigned pk2(float lo, float hi) { f32x2 v = {lo, hi}; bf16x2_t b = __builtin_convertvector(v, bf16x2_t); return __builtin_bit_cast(unsigned, b); }
; #define MFMA32(a, b, c) __builtin_amdgcn_mfma_f32_32x32x16_bf16((a), (b), (c), 0, 0, 0)
; #define SBAR() __builtin_amdgcn_sched_barrier(0)
; #define AT_WRITEK(slot) do { *(LAS u32x4*)(lds + (slot) * AT_K + kst) = rk; } while (0)
; DI void attn_step(const LAS unsigned char* Kb, const LAS unsigned char* Vb, f32x16& c0, f32x16& c1, f32x16& n0, f32x16& n1, bf16x8 (&pf)[2][2],
;                   f32x16 (&o)[4], f32x16& negm, float& mrun, float& lrun, const bf16x8 (&qf)[4]) {
;     ...
;     __builtin_amdgcn_s_setprio(1);
; #pragma unroll
;     for (int i = 4; i < 16; ++i) {
;         if (i + 3 < 16) vf[(i + 3) % 4] = AT_VF(i + 3);
;         o[i >> 2] = MFMA32(vf[i % 4], pf[(i >> 1) & 1][i & 1], o[i >> 2]);
;         const int j = i - 4, e0 = j < 8 ? 3 * j : 24 + 2 * (j - 8), ne = j < 8 ? 3 : 2;
; #pragma unroll
;         for (int e = e0; e < e0 + ne; ++e) { if (e < 16) c0[e & 15] = __builtin_amdgcn_exp2f(c0[e & 15]); else c1[e & 15] = __builtin_amdgcn_exp2f(c1[e & 15]); }
;         SBAR();
;     }
;     bf16x8 kf[4];
;     kf[0] = AT_KF(0); kf[1] = AT_KF(1); kf[2] = AT_KF(2);
;     float ls0 = 0.f, ls1 = 0.f; unsigned pw[16];
; #pragma unroll
;     for (int i = 0; i < 8; ++i) {
;         if (i + 3 < 8) kf[(i + 3) % 4] = AT_KF(i + 3);
;         if (i & 1) n1 = MFMA32(kf[i % 4], qf[i >> 1], i < 2 ? negm : n1); else n0 = MFMA32(kf[i % 4], qf[i >> 1], i < 2 ? negm : n0);
;         ls0 += AT_C(4 * i) + AT_C(4 * i + 1); ls1 += AT_C(4 * i + 2) + AT_C(4 * i + 3);
;         pw[2 * i] = pk2(AT_C(4 * i), AT_C(4 * i + 1)); pw[2 * i + 1] = pk2(AT_C(4 * i + 2), AT_C(4 * i + 3));
;         SBAR();
;     }
; #pragma unroll
;     for (int kh = 0; kh < 2; ++kh)
; #pragma unroll
;         for (int s2 = 0; s2 < 2; ++s2) { const u32x4 w = (u32x4){pw[8 * kh + 4 * s2], pw[8 * kh + 4 * s2 + 1], pw[8 * kh + 4 * s2 + 2], pw[8 * kh + 4 * s2 + 3]}; pf[kh][s2] = __builtin_bit_cast(bf16x8, w); }
;     __builtin_amdgcn_s_setprio(0);
;     lrun = lrun * sc + (ls0 + ls1);
; DI void attn_unit(LAS unsigned char* lds, const bf16_t* QK, const bf16_t* VT, bf16_t* O, int mp, int h, int q0, int kt0, int kt1, int coff, int wid0) {
;     ...
;         AT_WRITEK(0); AT_WRITEV(0);
;         __syncthreads();
.Lg1_459:
	s_waitcnt lgkmcnt(2)
	v_mfma_f32_32x32x16_bf16 v[32:47], v[172:175], v[148:151], v[32:47]
	ds_read_b128 v[80:83], v196 offset:41568
	v_exp_f32_e32 v92, v96
	v_exp_f32_e32 v93, v97
	v_exp_f32_e32 v94, v98
	s_waitcnt lgkmcnt(2)
	v_mfma_f32_32x32x16_bf16 v[32:47], v[176:179], v[144:147], v[32:47]
	ds_read_b128 v[84:87], v196 offset:46080
	v_exp_f32_e32 v95, v99
	v_exp_f32_e32 v172, v100
	v_exp_f32_e32 v173, v101
	s_waitcnt lgkmcnt(2)
	v_mfma_f32_32x32x16_bf16 v[32:47], v[180:183], v[152:155], v[32:47]
	ds_read_b128 v[96:99], v196 offset:46112
	v_exp_f32_e32 v174, v102
	v_exp_f32_e32 v175, v103
	v_exp_f32_e32 v176, v104
	s_waitcnt lgkmcnt(2)
	v_mfma_f32_32x32x16_bf16 v[32:47], v[80:83], v[156:159], v[32:47]
	ds_read_b128 v[100:103], v196 offset:46144
	v_exp_f32_e32 v177, v105
	v_exp_f32_e32 v178, v106
	v_exp_f32_e32 v179, v107
	s_waitcnt lgkmcnt(2)
	v_mfma_f32_32x32x16_bf16 v[16:31], v[84:87], v[148:151], v[16:31]
	ds_read_b128 v[104:107], v196 offset:46176
	v_exp_f32_e32 v180, v108
	v_exp_f32_e32 v181, v109
	v_exp_f32_e32 v182, v110
	s_waitcnt lgkmcnt(2)
	v_mfma_f32_32x32x16_bf16 v[16:31], v[96:99], v[144:147], v[16:31]
	ds_read_b128 v[80:83], v196 offset:50688
	v_exp_f32_e32 v183, v111
	v_exp_f32_e32 v218, v64
	v_exp_f32_e32 v219, v65
	s_waitcnt lgkmcnt(2)
	v_mfma_f32_32x32x16_bf16 v[16:31], v[100:103], v[152:155], v[16:31]
	ds_read_b128 v[96:99], v196 offset:50720
	v_exp_f32_e32 v222, v66
	v_exp_f32_e32 v223, v67
	v_exp_f32_e32 v224, v68
	s_waitcnt lgkmcnt(2)
	v_mfma_f32_32x32x16_bf16 v[16:31], v[104:107], v[156:159], v[16:31]
	ds_read_b128 v[64:67], v196 offset:50752
	v_exp_f32_e32 v225, v69
	v_exp_f32_e32 v226, v70
	v_exp_f32_e32 v227, v71
	s_waitcnt lgkmcnt(2)
	v_mfma_f32_32x32x16_bf16 v[0:15], v[80:83], v[148:151], v[0:15]
	ds_read_b128 v[68:71], v196 offset:50784
	v_exp_f32_e32 v228, v72
	v_exp_f32_e32 v229, v73
	s_waitcnt lgkmcnt(2)
	v_mfma_f32_32x32x16_bf16 v[0:15], v[96:99], v[144:147], v[0:15]
	v_exp_f32_e32 v230, v74
	v_exp_f32_e32 v231, v75
	s_waitcnt lgkmcnt(1)
	v_mfma_f32_32x32x16_bf16 v[0:15], v[64:67], v[152:155], v[0:15]
	v_exp_f32_e32 v232, v76
	v_exp_f32_e32 v233, v77
	s_waitcnt lgkmcnt(0)
	v_mfma_f32_32x32x16_bf16 v[0:15], v[68:71], v[156:159], v[0:15]
	v_exp_f32_e32 v159, v78
	v_exp_f32_e32 v234, v79
	ds_read_b128 v[64:67], v196 offset:9216
	ds_read_b128 v[80:83], v196 offset:9248
	ds_read_b128 v[84:87], v196 offset:13824
	ds_read_b128 v[88:91], v196 offset:13856
	v_cvt_pk_bf16_f32 v144, v92, v93
	s_waitcnt lgkmcnt(3)
	v_mfma_f32_32x32x16_bf16 v[96:111], v[64:67], v[128:131], v[112:127]
	v_add_f32_e32 v64, v93, v92
	v_add_f32_e32 v65, v95, v94
	v_cvt_pk_bf16_f32 v145, v94, v95
	v_add_f32_e32 v66, v173, v172
	v_add_f32_e32 v148, v66, v64
	v_add_f32_e32 v64, v175, v174
	v_add_f32_e32 v149, v64, v65
	s_waitcnt lgkmcnt(1)
	v_mfma_f32_32x32x16_bf16 v[64:79], v[84:87], v[128:131], v[112:127]
	ds_read_b128 v[92:95], v196 offset:9280
	s_waitcnt vmcnt(2)
	ds_write_b128 v195, v[168:171]
	v_cvt_pk_bf16_f32 v146, v172, v173
	v_cvt_pk_bf16_f32 v147, v174, v175
	v_mfma_f32_32x32x16_bf16 v[96:111], v[80:83], v[132:135], v[96:111]
	ds_read_b128 v[84:87], v196 offset:13888
	v_add_f32_e32 v80, v177, v176
	v_add_f32_e32 v150, v80, v148
	v_add_f32_e32 v80, v179, v178
	v_add_f32_e32 v151, v80, v149
	v_cvt_pk_bf16_f32 v148, v176, v177
	v_cvt_pk_bf16_f32 v149, v178, v179
	ds_read_b128 v[80:83], v196 offset:9312
	ds_read_b128 v[248:251], v196 offset:13920
	s_waitcnt vmcnt(1)
	ds_write2_b64 v244, v[164:165], v[166:167] offset1:2
	s_waitcnt lgkmcnt(6)
	v_mfma_f32_32x32x16_bf16 v[64:79], v[88:91], v[132:135], v[64:79]
	s_waitcnt vmcnt(0)
	ds_write2_b64 v245, v[160:161], v[162:163] offset0:128 offset1:130
	v_add_f32_e32 v88, v181, v180
	v_add_f32_e32 v152, v88, v150
	v_add_f32_e32 v88, v183, v182
	v_add_f32_e32 v153, v88, v151
	v_cvt_pk_bf16_f32 v150, v180, v181
	v_cvt_pk_bf16_f32 v151, v182, v183
	s_waitcnt lgkmcnt(0)
	s_barrier
	ds_read_b128 v[172:175], v196 offset:18432
	ds_read_b128 v[176:179], v196 offset:18464
	ds_read_b128 v[180:183], v196 offset:18496
	ds_read_b128 v[88:91], v196 offset:18528
	v_mfma_f32_32x32x16_bf16 v[96:111], v[92:95], v[136:139], v[96:111]
	v_add_f32_e32 v92, v219, v218
	v_add_f32_e32 v93, v223, v222
	v_add_f32_e32 v92, v92, v152
	v_add_f32_e32 v93, v93, v153
	v_cvt_pk_bf16_f32 v152, v218, v219
	v_cvt_pk_bf16_f32 v153, v222, v223
	v_mfma_f32_32x32x16_bf16 v[64:79], v[84:87], v[136:139], v[64:79]
	v_add_f32_e32 v84, v225, v224
	v_add_f32_e32 v85, v227, v226
	v_cvt_pk_bf16_f32 v154, v224, v225
	v_cvt_pk_bf16_f32 v155, v226, v227
	v_add_f32_e32 v84, v84, v92
	v_add_f32_e32 v85, v85, v93
	v_mfma_f32_32x32x16_bf16 v[96:111], v[80:83], v[140:143], v[96:111]
	v_add_f32_e32 v80, v229, v228
	v_add_f32_e32 v81, v231, v230
	v_cvt_pk_bf16_f32 v156, v228, v229
	v_cvt_pk_bf16_f32 v157, v230, v231
	v_add_f32_e32 v80, v80, v84
	v_add_f32_e32 v81, v81, v85
	v_mfma_f32_32x32x16_bf16 v[64:79], v[248:251], v[140:143], v[64:79]
	v_add_f32_e32 v82, v233, v232
	v_add_f32_e32 v80, v82, v80
	v_add_f32_e32 v82, v234, v159
	v_cvt_pk_bf16_f32 v158, v232, v233
	v_cvt_pk_bf16_f32 v159, v159, v234
	v_add_f32_e32 v81, v82, v81
	v_add_f32_e32 v222, v81, v80
	v_fmac_f32_e32 v222, v221, v194
	s_andn2_b64 vcc, exec, s[8:9]
	s_cbranch_vccz .Lg1_468

; DI unsigned pk2(float lo, float hi) { f32x2 v = {lo, hi}; bf16x2_t b = __builtin_convertvector(v, bf16x2_t); return __builtin_bit_cast(unsigned, b); }
; #define MFMA32(a, b, c) __builtin_amdgcn_mfma_f32_32x32x16_bf16((a), (b), (c), 0, 0, 0)
; #define SBAR() __builtin_amdgcn_sched_barrier(0)
; #define AT_WRITEK(slot) do { *(LAS u32x4*)(lds + (slot) * AT_K + kst) = rk; } while (0)
; DI void attn_step(const LAS unsigned char* Kb, const LAS unsigned char* Vb, f32x16& c0, f32x16& c1, f32x16& n0, f32x16& n1, bf16x8 (&pf)[2][2],
;                   f32x16 (&o)[4], f32x16& negm, float& mrun, float& lrun, const bf16x8 (&qf)[4]) {
;     ...
;     __builtin_amdgcn_s_setprio(1);
; #pragma unroll
;     for (int i = 4; i < 16; ++i) {
;         if (i + 3 < 16) vf[(i + 3) % 4] = AT_VF(i + 3);
;         o[i >> 2] = MFMA32(vf[i % 4], pf[(i >> 1) & 1][i & 1], o[i >> 2]);
;         const int j = i - 4, e0 = j < 8 ? 3 * j : 24 + 2 * (j - 8), ne = j < 8 ? 3 : 2;
; #pragma unroll
;         for (int e = e0; e < e0 + ne; ++e) { if (e < 16) c0[e & 15] = __builtin_amdgcn_exp2f(c0[e & 15]); else c1[e & 15] = __builtin_amdgcn_exp2f(c1[e & 15]); }
;         SBAR();
;     }
;     bf16x8 kf[4];
;     kf[0] = AT_KF(0); kf[1] = AT_KF(1); kf[2] = AT_KF(2);
;     float ls0 = 0.f, ls1 = 0.f; unsigned pw[16];
; #pragma unroll
;     for (int i = 0; i < 8; ++i) {
;         if (i + 3 < 8) kf[(i + 3) % 4] = AT_KF(i + 3);
;         if (i & 1) n1 = MFMA32(kf[i % 4], qf[i >> 1], i < 2 ? negm : n1); else n0 = MFMA32(kf[i % 4], qf[i >> 1], i < 2 ? negm : n0);
;         ls0 += AT_C(4 * i) + AT_C(4 * i + 1); ls1 += AT_C(4 * i + 2) + AT_C(4 * i + 3);
;         pw[2 * i] = pk2(AT_C(4 * i), AT_C(4 * i + 1)); pw[2 * i + 1] = pk2(AT_C(4 * i + 2), AT_C(4 * i + 3));
;         SBAR();
;     }
; #pragma unroll
;     for (int kh = 0; kh < 2; ++kh)
; #pragma unroll
;         for (int s2 = 0; s2 < 2; ++s2) { const u32x4 w = (u32x4){pw[8 * kh + 4 * s2], pw[8 * kh + 4 * s2 + 1], pw[8 * kh + 4 * s2 + 2], pw[8 * kh + 4 * s2 + 3]}; pf[kh][s2] = __builtin_bit_cast(bf16x8, w); }
;     __builtin_amdgcn_s_setprio(0);
;     lrun = lrun * sc + (ls0 + ls1);
; DI void attn_unit(LAS unsigned char* lds, const bf16_t* QK, const bf16_t* VT, bf16_t* O, int mp, int h, int q0, int kt0, int kt1, int coff, int wid0) {
;     ...
;         AT_WRITEK(1); AT_WRITEV(1);
;         __syncthreads();
.Lg1_464:
	s_waitcnt lgkmcnt(2)
	v_mfma_f32_32x32x16_bf16 v[32:47], v[172:175], v[144:147], v[32:47]
	ds_read_b128 v[80:83], v196 offset:23136
	v_exp_f32_e32 v172, v96
	v_exp_f32_e32 v173, v97
	v_exp_f32_e32 v174, v98
	s_waitcnt lgkmcnt(2)
	v_mfma_f32_32x32x16_bf16 v[32:47], v[176:179], v[148:151], v[32:47]
	ds_read_b128 v[84:87], v196 offset:27648
	v_exp_f32_e32 v175, v99
	v_exp_f32_e32 v176, v100
	v_exp_f32_e32 v177, v101
	s_waitcnt lgkmcnt(2)
	v_mfma_f32_32x32x16_bf16 v[32:47], v[180:183], v[152:155], v[32:47]
	ds_read_b128 v[88:91], v196 offset:27680
	v_exp_f32_e32 v178, v102
	v_exp_f32_e32 v179, v103
	v_exp_f32_e32 v180, v104
	s_waitcnt lgkmcnt(2)
	v_mfma_f32_32x32x16_bf16 v[32:47], v[80:83], v[156:159], v[32:47]
	ds_read_b128 v[92:95], v196 offset:27712
	v_exp_f32_e32 v181, v105
	v_exp_f32_e32 v182, v106
	v_exp_f32_e32 v183, v107
	s_waitcnt lgkmcnt(2)
	v_mfma_f32_32x32x16_bf16 v[16:31], v[84:87], v[144:147], v[16:31]
	ds_read_b128 v[80:83], v196 offset:27744
	v_exp_f32_e32 v239, v108
	v_exp_f32_e32 v218, v109
	v_exp_f32_e32 v219, v110
	s_waitcnt lgkmcnt(2)
	v_mfma_f32_32x32x16_bf16 v[16:31], v[88:91], v[148:151], v[16:31]
	ds_read_b128 v[84:87], v196 offset:32256
	v_exp_f32_e32 v221, v111
	v_exp_f32_e32 v224, v64
	v_exp_f32_e32 v225, v65
	s_waitcnt lgkmcnt(2)
	v_mfma_f32_32x32x16_bf16 v[16:31], v[92:95], v[152:155], v[16:31]
	ds_read_b128 v[88:91], v196 offset:32288
	v_exp_f32_e32 v226, v66
	v_exp_f32_e32 v227, v67
	v_exp_f32_e32 v228, v68
	s_waitcnt lgkmcnt(2)
	v_mfma_f32_32x32x16_bf16 v[16:31], v[80:83], v[156:159], v[16:31]
	ds_read_b128 v[64:67], v196 offset:32320
	v_exp_f32_e32 v229, v69
	v_exp_f32_e32 v230, v70
	v_exp_f32_e32 v231, v71
	s_waitcnt lgkmcnt(2)
	v_mfma_f32_32x32x16_bf16 v[0:15], v[84:87], v[144:147], v[0:15]
	ds_read_b128 v[68:71], v196 offset:32352
	v_exp_f32_e32 v232, v72
	v_exp_f32_e32 v233, v73
	s_waitcnt lgkmcnt(2)
	v_mfma_f32_32x32x16_bf16 v[0:15], v[88:91], v[148:151], v[0:15]
	v_exp_f32_e32 v234, v74
	v_exp_f32_e32 v235, v75
	s_waitcnt lgkmcnt(1)
	v_mfma_f32_32x32x16_bf16 v[0:15], v[64:67], v[152:155], v[0:15]
	v_exp_f32_e32 v236, v76
	v_exp_f32_e32 v237, v77
	s_waitcnt lgkmcnt(0)
	v_mfma_f32_32x32x16_bf16 v[0:15], v[68:71], v[156:159], v[0:15]
	v_exp_f32_e32 v159, v78
	v_exp_f32_e32 v238, v79
	ds_read_b128 v[64:67], v196
	ds_read_b128 v[80:83], v196 offset:32
	ds_read_b128 v[84:87], v196 offset:4608
	ds_read_b128 v[88:91], v196 offset:4640
	v_cvt_pk_bf16_f32 v148, v172, v173
	s_waitcnt lgkmcnt(3)
	v_mfma_f32_32x32x16_bf16 v[96:111], v[64:67], v[128:131], v[112:127]
	v_add_f32_e32 v64, v173, v172
	v_add_f32_e32 v65, v175, v174
	v_cvt_pk_bf16_f32 v149, v174, v175
	v_add_f32_e32 v66, v177, v176
	v_add_f32_e32 v144, v66, v64
	v_add_f32_e32 v64, v179, v178
	v_add_f32_e32 v145, v64, v65
	s_waitcnt lgkmcnt(1)
	v_mfma_f32_32x32x16_bf16 v[64:79], v[84:87], v[128:131], v[112:127]
	ds_read_b128 v[92:95], v196 offset:64
	s_waitcnt vmcnt(2)
	ds_write_b128 v195, v[168:171] offset:9216
	v_cvt_pk_bf16_f32 v150, v176, v177
	v_cvt_pk_bf16_f32 v151, v178, v179
	v_mfma_f32_32x32x16_bf16 v[96:111], v[80:83], v[132:135], v[96:111]
	ds_read_b128 v[84:87], v196 offset:4672
	v_add_f32_e32 v80, v181, v180
	v_add_f32_e32 v146, v80, v144
	v_add_f32_e32 v80, v183, v182
	v_add_f32_e32 v147, v80, v145
	v_cvt_pk_bf16_f32 v144, v180, v181
	v_cvt_pk_bf16_f32 v145, v182, v183
	ds_read_b128 v[80:83], v196 offset:96
	ds_read_b128 v[248:251], v196 offset:4704
	s_waitcnt vmcnt(1)
	ds_write2_b64 v246, v[164:165], v[166:167] offset1:2
	s_waitcnt lgkmcnt(6)
	v_mfma_f32_32x32x16_bf16 v[64:79], v[88:91], v[132:135], v[64:79]
	s_waitcnt vmcnt(0)
	ds_write2_b64 v247, v[160:161], v[162:163] offset0:128 offset1:130
	v_add_f32_e32 v88, v218, v239
	v_add_f32_e32 v152, v88, v146
	v_add_f32_e32 v88, v221, v219
	v_add_f32_e32 v153, v88, v147
	v_cvt_pk_bf16_f32 v146, v239, v218
	v_cvt_pk_bf16_f32 v147, v219, v221
	s_waitcnt lgkmcnt(0)
	s_barrier
	ds_read_b128 v[172:175], v196 offset:36864
	ds_read_b128 v[176:179], v196 offset:36896
	ds_read_b128 v[180:183], v196 offset:36928
	ds_read_b128 v[88:91], v196 offset:36960
	v_mfma_f32_32x32x16_bf16 v[96:111], v[92:95], v[136:139], v[96:111]
	v_add_f32_e32 v92, v225, v224
	v_add_f32_e32 v93, v227, v226
	v_add_f32_e32 v92, v92, v152
	v_add_f32_e32 v93, v93, v153
	v_cvt_pk_bf16_f32 v152, v224, v225
	v_cvt_pk_bf16_f32 v153, v226, v227
	v_mfma_f32_32x32x16_bf16 v[64:79], v[84:87], v[136:139], v[64:79]
	v_add_f32_e32 v84, v229, v228
	v_add_f32_e32 v85, v231, v230
	v_cvt_pk_bf16_f32 v154, v228, v229
	v_cvt_pk_bf16_f32 v155, v230, v231
	v_add_f32_e32 v84, v84, v92
	v_add_f32_e32 v85, v85, v93
	v_mfma_f32_32x32x16_bf16 v[96:111], v[80:83], v[140:143], v[96:111]
	v_add_f32_e32 v80, v233, v232
	v_add_f32_e32 v81, v235, v234
	v_cvt_pk_bf16_f32 v156, v232, v233
	v_cvt_pk_bf16_f32 v157, v234, v235
	v_add_f32_e32 v80, v80, v84
	v_add_f32_e32 v81, v81, v85
	v_mfma_f32_32x32x16_bf16 v[64:79], v[248:251], v[140:143], v[64:79]
	v_add_f32_e32 v82, v237, v236
	v_add_f32_e32 v80, v82, v80
	v_add_f32_e32 v82, v238, v159
	v_cvt_pk_bf16_f32 v158, v236, v237
	v_cvt_pk_bf16_f32 v159, v159, v238
	v_add_f32_e32 v81, v82, v81
	v_add_f32_e32 v221, v81, v80
	v_fmac_f32_e32 v221, v222, v194
	s_andn2_b64 vcc, exec, s[8:9]
	s_cbranch_vccz .Lg1_470
